# grid barrier release flattened: last XCD leader bumps all per-XCD generation words, TOPGEN hop removed
# speedup vs baseline: 1.0108x; 1.0047x over previous
; DEV unsigned xb_ld(unsigned* p) { return __hip_atomic_load(p, __ATOMIC_RELAXED, __HIP_MEMORY_SCOPE_AGENT); }
; DEV unsigned xb_add(unsigned* p, unsigned v) { return __hip_atomic_fetch_add(p, v, __ATOMIC_RELAXED, __HIP_MEMORY_SCOPE_AGENT); }
; #define XB_SPIN(cond, bar) do { unsigned _sp = 0; while (cond) { __builtin_amdgcn_s_sleep(1); \
;     if ((++_sp & 255u) == 0u) { if (xb_ld(&(bar)[XB_TMO])) break; if (_sp > XB_SPIN_CAP) { atomicAdd(&(bar)[XB_TMO], 1u); break; } } } } while (0)
; DEV void xcd_barrier(XcdBarrier& b) {
;   asm volatile("s_waitcnt vmcnt(0)" ::: "memory");
;   __syncthreads();
;   if (threadIdx.x == 0) {
;     unsigned* bar = b.bar;
;     __builtin_amdgcn_s_waitcnt(0);
;     unsigned nloc = b.nloc, nx = b.nx;
;     if (nloc == 0u) { xcd_barrier_complete(bar, b.x, nloc, nx); b.nloc = nloc; b.nx = nx; }
;     const unsigned old = xb_add(&bar[XB_XSUB(b.x)], 1u);
;     const unsigned gen = old / nloc;
;     if (old + 1u == (gen + 1u) * nloc) {
;       __builtin_amdgcn_fence(__ATOMIC_RELEASE, "agent");
;       asm volatile("s_waitcnt vmcnt(0)" ::: "memory");
;       const unsigned og = xb_add(&bar[XB_TOP], 1u);
;       const unsigned tg = og / nx;
;       if (og + 1u == (tg + 1u) * nx) xb_add(&bar[XB_TOPGEN], 1u);
;       else XB_SPIN(xb_ld(&bar[XB_TOPGEN]) == tg, bar);
;       __builtin_amdgcn_fence(__ATOMIC_ACQUIRE, "agent");
;       xb_add(&bar[XB_XGEN(b.x)], 1u);
;       asm volatile("s_waitcnt vmcnt(0)" ::: "memory");
;     } else {
;       XB_SPIN(xb_ld(&bar[XB_XGEN(b.x)]) == gen, bar);
;       __builtin_amdgcn_fence(__ATOMIC_ACQUIRE, "agent");
;       asm volatile("s_waitcnt vmcnt(0)" ::: "memory");
;     }
;   }
;   __syncthreads();
; }
.LBB0_1529:
	s_or_b64 exec, exec, s[0:1]
	v_readlane_b32 s4, v254, 4
	v_readlane_b32 s5, v254, 5
	v_mov_b32_e32 v1, 1
	s_nop 4
	global_atomic_add v1, v133, v1, s[4:5] sc0
	s_waitcnt vmcnt(0)
	v_sub_u32_e32 v2, 0, v138
	v_cvt_f32_u32_e32 v0, v138
	v_rcp_iflag_f32_e32 v0, v0
	s_nop 0
	v_mul_f32_e32 v0, 0x4f7ffffe, v0
	v_cvt_u32_f32_e32 v0, v0
	v_mul_lo_u32 v2, v2, v0
	v_mul_hi_u32 v2, v0, v2
	v_add_u32_e32 v0, v0, v2
	v_mul_hi_u32 v0, v1, v0
	v_mul_lo_u32 v2, v0, v138
	v_sub_u32_e32 v2, v1, v2
	v_cmp_ge_u32_e32 vcc, v2, v138
	v_add_u32_e32 v3, 1, v0
	v_add_u32_e32 v1, 1, v1
	v_cndmask_b32_e32 v0, v0, v3, vcc
	v_sub_u32_e32 v3, v2, v138
	v_cndmask_b32_e32 v2, v2, v3, vcc
	v_cmp_ge_u32_e32 vcc, v2, v138
	v_add_u32_e32 v2, 1, v0
	s_nop 0
	v_cndmask_b32_e32 v0, v0, v2, vcc
	v_mad_u64_u32 v[2:3], s[8:9], v138, v0, v[138:139]
	v_cmp_ne_u32_e32 vcc, v1, v2
	s_cbranch_vccnz .Lxb_spin
	buffer_wbl2 sc1
	s_waitcnt vmcnt(0)
	v_readlane_b32 s4, v254, 8
	v_readlane_b32 s5, v254, 9
	v_mov_b32_e32 v5, 1
	s_nop 4
	global_atomic_add v5, v133, v5, s[4:5] sc0
	s_waitcnt vmcnt(0)
	v_sub_u32_e32 v6, 0, v136
	v_cvt_f32_u32_e32 v4, v136
	v_rcp_iflag_f32_e32 v4, v4
	s_nop 0
	v_mul_f32_e32 v4, 0x4f7ffffe, v4
	v_cvt_u32_f32_e32 v4, v4
	v_mul_lo_u32 v6, v6, v4
	v_mul_hi_u32 v6, v4, v6
	v_add_u32_e32 v4, v4, v6
	v_mul_hi_u32 v4, v5, v4
	v_mul_lo_u32 v6, v4, v136
	v_sub_u32_e32 v6, v5, v6
	v_cmp_ge_u32_e32 vcc, v6, v136
	v_add_u32_e32 v7, 1, v4
	v_add_u32_e32 v5, 1, v5
	v_cndmask_b32_e32 v4, v4, v7, vcc
	v_sub_u32_e32 v7, v6, v136
	v_cndmask_b32_e32 v6, v6, v7, vcc
	v_cmp_ge_u32_e32 vcc, v6, v136
	v_add_u32_e32 v6, 1, v4
	s_nop 0
	v_cndmask_b32_e32 v4, v4, v6, vcc
	v_mad_u64_u32 v[6:7], s[8:9], v136, v4, v[136:137]
	v_cmp_ne_u32_e32 vcc, v5, v6
	s_cbranch_vccnz .Lxb_spin
	s_sub_u32 s4, s4, 0x1000
	s_subb_u32 s5, s5, 0
	v_mov_b32_e32 v5, 1
	global_atomic_add v133, v5, s[4:5]
	global_atomic_add v133, v5, s[4:5] offset:256
	global_atomic_add v133, v5, s[4:5] offset:512
	global_atomic_add v133, v5, s[4:5] offset:768
	global_atomic_add v133, v5, s[4:5] offset:1024
	global_atomic_add v133, v5, s[4:5] offset:1280
	global_atomic_add v133, v5, s[4:5] offset:1536
	global_atomic_add v133, v5, s[4:5] offset:1792
	global_atomic_add v133, v5, s[4:5] offset:2048
	global_atomic_add v133, v5, s[4:5] offset:2304
	global_atomic_add v133, v5, s[4:5] offset:2560
	global_atomic_add v133, v5, s[4:5] offset:2816
	global_atomic_add v133, v5, s[4:5] offset:3072
	global_atomic_add v133, v5, s[4:5] offset:3328
	global_atomic_add v133, v5, s[4:5] offset:3584
	global_atomic_add v133, v5, s[4:5] offset:3840
	s_branch .Lxb_rel
.Lxb_spin:
	v_readlane_b32 s6, v254, 6
	v_readlane_b32 s7, v254, 7
	v_readlane_b32 s8, v253, 2
	v_readlane_b32 s9, v253, 3
	s_mov_b32 s16, 0
	s_nop 3
.Lxb_loop:
	global_load_dword v1, v133, s[6:7] sc1
	s_waitcnt vmcnt(0)
	v_cmp_ne_u32_e32 vcc, v1, v0
	s_cbranch_vccnz .Lxb_rel
	s_sleep 1
	s_add_i32 s16, s16, 1
	s_and_b32 s12, s16, 0xff
	s_cmp_lg_u32 s12, 0
	s_cbranch_scc1 .Lxb_loop
	global_load_dword v1, v133, s[8:9] sc1
	s_waitcnt vmcnt(0)
	v_cmp_ne_u32_e32 vcc, 0, v1
	s_cbranch_vccnz .Lxb_rel
	s_cmp_lt_u32 s16, 0x100001
	s_cbranch_scc1 .Lxb_loop
	v_mov_b32_e32 v1, 1
	global_atomic_add v133, v1, s[8:9]
.Lxb_rel:
	s_waitcnt vmcnt(0)
	buffer_inv sc1
	s_waitcnt vmcnt(0)
